# v33 + attention row-sum chains (GQA and diff loops) accumulate two lanes with v_pk_add_f32 (f32), 16 instead of 31 adds per tile
# baseline (speedup 1.0000x reference)
; #define WAIT_BAR(N) asm volatile("s_waitcnt vmcnt(" #N ") lgkmcnt(0)\n\ts_barrier" ::: "memory")
;   #define RESC() do { if constexpr (!NOMAX) if (resc) { asm volatile("s_waitcnt lgkmcnt(0)" ::: "memory"); \
;       _Pragma("unroll") for (int d_ = 0; d_ < 2 * DV2; ++d_) _Pragma("unroll") for (int r = 0; r < 16; ++r) o[d_][r] *= wsf[crow(r, hi)]; } } while (0)
;   #define ROT() do { sl_prev = sl_cur; sl_cur = sl_next; sl_next = (sl_next == (NSLOT - 1) * SLOTB) ? 0 : sl_next + SLOTB; } while (0)
;     ...
;   for (; t + 5 < NT; t += 2) {
;     STEP(pB0, pB1, pA0, pA1, t, true, true, true);     if constexpr (DV2 == 2) { WAIT_BAR(3); } else { WAIT_BAR(2); } RESC(); ROT();
;     STEP(pA0, pA1, pB0, pB1, t + 1, true, true, true); if constexpr (DV2 == 2) { WAIT_BAR(3); } else { WAIT_BAR(2); } RESC(); ROT();
;   }
.LBB0_477:
	s_lshl_b32 s22, s22, 1
	v_add_u32_e32 v212, s22, v245
	ds_read_b64_tr_b16 v[208:209], v212 offset:24576
	ds_read_b64_tr_b16 v[210:211], v212 offset:25088
	v_mfma_f32_32x32x16_bf16 v[128:143], v[204:207], v[172:175], v[64:79]
	v_pk_add_f32 v[112:113], v[96:97], v[98:99]
	v_pk_add_f32 v[112:113], v[100:101], v[112:113]
	v_cvt_pk_bf16_f32 v156, v96, v97
	v_cvt_pk_bf16_f32 v157, v98, v99
	ds_read_b64_tr_b16 v[204:205], v212 offset:28672
	ds_read_b64_tr_b16 v[206:207], v212 offset:29184
	v_pk_add_f32 v[96:97], v[102:103], v[112:113]
	v_mfma_f32_32x32x16_bf16 v[112:127], v[196:199], v[172:175], v[64:79]
	v_pk_add_f32 v[96:97], v[104:105], v[96:97]
	v_cvt_pk_bf16_f32 v158, v100, v101
	v_cvt_pk_bf16_f32 v159, v102, v103
	ds_read_b64_tr_b16 v[100:101], v212 offset:25600
	ds_read_b64_tr_b16 v[102:103], v212 offset:26112
	v_mfma_f32_32x32x16_bf16 v[128:143], v[200:203], v[168:171], v[128:143]
	v_pk_add_f32 v[96:97], v[106:107], v[96:97]
	v_pk_add_f32 v[144:145], v[108:109], v[96:97]
	v_cvt_pk_bf16_f32 v152, v104, v105
	v_cvt_pk_bf16_f32 v153, v106, v107
	ds_read_b64_tr_b16 v[96:97], v212 offset:29696
	ds_read_b64_tr_b16 v[98:99], v212 offset:30208
	v_mfma_f32_32x32x16_bf16 v[112:127], v[192:195], v[168:171], v[112:127]
	v_pk_add_f32 v[104:105], v[110:111], v[144:145]
	v_pk_add_f32 v[104:105], v[80:81], v[104:105]
	v_cvt_pk_bf16_f32 v154, v108, v109
	v_cvt_pk_bf16_f32 v155, v110, v111
	ds_read_b64_tr_b16 v[108:109], v212 offset:26624
	ds_read_b64_tr_b16 v[110:111], v212 offset:27136
	v_mfma_f32_32x32x16_bf16 v[128:143], v[188:191], v[164:167], v[128:143]
	v_pk_add_f32 v[104:105], v[82:83], v[104:105]
	v_pk_add_f32 v[144:145], v[84:85], v[104:105]
	v_cvt_pk_bf16_f32 v148, v80, v81
	v_cvt_pk_bf16_f32 v149, v82, v83
	ds_read_b64_tr_b16 v[104:105], v212 offset:30720
	ds_read_b64_tr_b16 v[106:107], v212 offset:31232
	v_mfma_f32_32x32x16_bf16 v[112:127], v[184:187], v[164:167], v[112:127]
	v_pk_add_f32 v[80:81], v[86:87], v[144:145]
	v_pk_add_f32 v[80:81], v[88:89], v[80:81]
	v_cvt_pk_bf16_f32 v150, v84, v85
	v_cvt_pk_bf16_f32 v151, v86, v87
	ds_read_b64_tr_b16 v[84:85], v212 offset:27648
	ds_read_b64_tr_b16 v[86:87], v212 offset:28160
	v_mfma_f32_32x32x16_bf16 v[128:143], v[180:183], v[160:163], v[128:143]
	v_pk_add_f32 v[80:81], v[90:91], v[80:81]
	v_pk_add_f32 v[80:81], v[92:93], v[80:81]
	v_cvt_pk_bf16_f32 v144, v88, v89
	v_cvt_pk_bf16_f32 v145, v90, v91
	ds_read_b64_tr_b16 v[88:89], v212 offset:31744
	ds_read_b64_tr_b16 v[90:91], v212 offset:32256
	v_mfma_f32_32x32x16_bf16 v[112:127], v[176:179], v[160:163], v[112:127]
	v_pk_add_f32 v[80:81], v[94:95], v[80:81]
	v_add_f32_e32 v80, v80, v81
	v_cvt_pk_bf16_f32 v146, v92, v93
	v_cvt_pk_bf16_f32 v147, v94, v95
	s_waitcnt lgkmcnt(14)
	v_mfma_f32_32x32x16_bf16 v[0:15], v[156:159], v[208:211], v[0:15]
	v_max_f32_e32 v81, v129, v129
	v_max_f32_e32 v82, v128, v128
	v_max_f32_e32 v81, v82, v81
	s_nop 3
	v_max3_f32 v82, v130, v131, v113
	v_max3_f32 v81, v81, v112, v114
	v_max3_f32 v81, v81, v115, v132
	v_max3_f32 v82, v82, v134, v135
	s_waitcnt lgkmcnt(12)
	v_mfma_f32_32x32x16_bf16 v[48:63], v[156:159], v[204:207], v[48:63]
	s_add_u32 s37, s16, s24
	v_max3_f32 v81, v81, v133, v116
	v_max3_f32 v82, v82, v118, v119
	s_addc_u32 s39, s17, s19
	v_max3_f32 v81, v81, v117, v136
	v_max3_f32 v82, v82, v138, v139
	s_add_u32 s22, s37, 0x9b80800
	v_max3_f32 v81, v81, v137, v120
	v_max3_f32 v82, v82, v122, v123
	s_addc_u32 s23, s39, 0
	s_add_i32 s34, s33, s28
	s_mov_b32 m0, s34
	s_nop 0
	global_load_lds_dwordx4 v241, s[22:23]
	v_max3_f32 v81, v81, v121, v140
	v_max3_f32 v82, v82, v142, v143
	s_add_u32 s35, s20, s24
	v_max3_f32 v81, v81, v141, v124
	v_max3_f32 v82, v82, v126, v127
	s_addc_u32 s36, s21, s19
	v_add_f32_e32 v251, v251, v80
	v_max3_f32 v80, v81, v125, v82
	s_add_u32 s22, s35, 0x9ac1000
	v_mov_b32_e32 v81, v80
	s_addc_u32 s23, s36, 0
	s_lshl_b32 s34, s31, 1
	v_permlane32_swap_b32_e32 v80, v81
	s_add_i32 s34, s34, s29
	s_mov_b32 m0, s34
	s_nop 0
	global_load_lds_dwordx4 v242, s[22:23]
	s_add_u32 s22, s35, 0x9ac1080
	v_max_f32_e32 v80, v80, v81
	s_addc_u32 s23, s36, 0
	s_addk_i32 s34, 0x2000
	s_mov_b32 m0, s34
	s_nop 0
	global_load_lds_dwordx4 v242, s[22:23]
	v_cmp_lt_f32_e32 vcc, s25, v80
	s_cmp_lg_u64 vcc, 0
	s_cselect_b64 s[22:23], -1, 0
	s_cbranch_vccnz .LBB0_485

; #define WAIT_BAR(N) asm volatile("s_waitcnt vmcnt(" #N ") lgkmcnt(0)\n\ts_barrier" ::: "memory")
;   #define RESC() do { if constexpr (!NOMAX) if (resc) { asm volatile("s_waitcnt lgkmcnt(0)" ::: "memory"); \
;       _Pragma("unroll") for (int d_ = 0; d_ < 2 * DV2; ++d_) _Pragma("unroll") for (int r = 0; r < 16; ++r) o[d_][r] *= wsf[crow(r, hi)]; } } while (0)
;   #define ROT() do { sl_prev = sl_cur; sl_cur = sl_next; sl_next = (sl_next == (NSLOT - 1) * SLOTB) ? 0 : sl_next + SLOTB; } while (0)
;     ...
;   for (; t + 5 < NT; t += 2) {
;     STEP(pB0, pB1, pA0, pA1, t, true, true, true);     if constexpr (DV2 == 2) { WAIT_BAR(3); } else { WAIT_BAR(2); } RESC(); ROT();
;     STEP(pA0, pA1, pB0, pB1, t + 1, true, true, true); if constexpr (DV2 == 2) { WAIT_BAR(3); } else { WAIT_BAR(2); } RESC(); ROT();
;   }
.LBB0_480:
	s_add_i32 s22, s31, 0x2000
	s_cmpk_lg_i32 s31, 0x4000
	s_cselect_b32 s34, s22, 0
	s_lshl_b32 s22, s33, 1
	v_add_u32_e32 v236, s22, v245
	ds_read_b64_tr_b16 v[212:213], v236 offset:24576
	ds_read_b64_tr_b16 v[214:215], v236 offset:25088
	v_mfma_f32_32x32x16_bf16 v[96:111], v[80:83], v[172:175], v[64:79]
	v_pk_add_f32 v[84:85], v[128:129], v[130:131]
	v_pk_add_f32 v[84:85], v[132:133], v[84:85]
	v_cvt_pk_bf16_f32 v156, v128, v129
	v_cvt_pk_bf16_f32 v157, v130, v131
	ds_read_b64_tr_b16 v[204:205], v236 offset:28672
	ds_read_b64_tr_b16 v[206:207], v236 offset:29184
	v_pk_add_f32 v[128:129], v[134:135], v[84:85]
	v_pk_add_f32 v[128:129], v[136:137], v[128:129]
	v_mfma_f32_32x32x16_bf16 v[80:95], v[196:199], v[172:175], v[64:79]
	v_cvt_pk_bf16_f32 v158, v132, v133
	v_cvt_pk_bf16_f32 v159, v134, v135
	ds_read_b64_tr_b16 v[208:209], v236 offset:25600
	ds_read_b64_tr_b16 v[210:211], v236 offset:26112
	v_mfma_f32_32x32x16_bf16 v[96:111], v[200:203], v[168:171], v[96:111]
	v_pk_add_f32 v[128:129], v[138:139], v[128:129]
	v_pk_add_f32 v[128:129], v[140:141], v[128:129]
	v_cvt_pk_bf16_f32 v152, v136, v137
	v_cvt_pk_bf16_f32 v153, v138, v139
	ds_read_b64_tr_b16 v[132:133], v236 offset:29696
	ds_read_b64_tr_b16 v[134:135], v236 offset:30208
	v_mfma_f32_32x32x16_bf16 v[80:95], v[192:195], v[168:171], v[80:95]
	v_pk_add_f32 v[128:129], v[142:143], v[128:129]
	v_pk_add_f32 v[136:137], v[112:113], v[128:129]
	v_cvt_pk_bf16_f32 v154, v140, v141
	v_cvt_pk_bf16_f32 v155, v142, v143
	ds_read_b64_tr_b16 v[128:129], v236 offset:26624
	ds_read_b64_tr_b16 v[130:131], v236 offset:27136
	v_mfma_f32_32x32x16_bf16 v[96:111], v[188:191], v[164:167], v[96:111]
	v_pk_add_f32 v[136:137], v[114:115], v[136:137]
	v_pk_add_f32 v[136:137], v[116:117], v[136:137]
	v_cvt_pk_bf16_f32 v148, v112, v113
	v_cvt_pk_bf16_f32 v149, v114, v115
	ds_read_b64_tr_b16 v[112:113], v236 offset:30720
	ds_read_b64_tr_b16 v[114:115], v236 offset:31232
	v_mfma_f32_32x32x16_bf16 v[80:95], v[184:187], v[164:167], v[80:95]
	v_pk_add_f32 v[136:137], v[118:119], v[136:137]
	v_pk_add_f32 v[136:137], v[120:121], v[136:137]
	v_cvt_pk_bf16_f32 v150, v116, v117
	v_cvt_pk_bf16_f32 v151, v118, v119
	ds_read_b64_tr_b16 v[116:117], v236 offset:27648
	ds_read_b64_tr_b16 v[118:119], v236 offset:28160
	v_mfma_f32_32x32x16_bf16 v[96:111], v[180:183], v[160:163], v[96:111]
	v_pk_add_f32 v[136:137], v[122:123], v[136:137]
	v_pk_add_f32 v[136:137], v[124:125], v[136:137]
	v_cvt_pk_bf16_f32 v144, v120, v121
	v_cvt_pk_bf16_f32 v145, v122, v123
	ds_read_b64_tr_b16 v[120:121], v236 offset:31744
	ds_read_b64_tr_b16 v[122:123], v236 offset:32256
	v_mfma_f32_32x32x16_bf16 v[80:95], v[176:179], v[160:163], v[80:95]
	v_pk_add_f32 v[136:137], v[126:127], v[136:137]
	v_add_f32_e32 v136, v136, v137
	v_cvt_pk_bf16_f32 v146, v124, v125
	v_cvt_pk_bf16_f32 v147, v126, v127
	s_waitcnt lgkmcnt(14)
	v_mfma_f32_32x32x16_bf16 v[0:15], v[156:159], v[212:215], v[0:15]
	v_max_f32_e32 v124, v97, v97
	v_max_f32_e32 v125, v96, v96
	v_max_f32_e32 v124, v125, v124
	s_nop 3
	v_max3_f32 v125, v98, v99, v81
	v_max3_f32 v124, v124, v80, v82
	v_max3_f32 v124, v124, v83, v100
	v_max3_f32 v125, v125, v102, v103
	s_waitcnt lgkmcnt(12)
	v_mfma_f32_32x32x16_bf16 v[48:63], v[156:159], v[204:207], v[48:63]
	v_max3_f32 v124, v124, v101, v84
	v_max3_f32 v125, v125, v86, v87
	v_max3_f32 v124, v124, v85, v104
	v_max3_f32 v125, v125, v106, v107
	v_max3_f32 v124, v124, v105, v88
	v_max3_f32 v125, v125, v90, v91
	v_max3_f32 v124, v124, v89, v108
	v_max3_f32 v125, v125, v110, v111
	s_add_u32 s22, s37, 0x9be0800
	v_max3_f32 v124, v124, v109, v92
	v_max3_f32 v125, v125, v94, v95
	s_addc_u32 s23, s39, 0
	s_add_i32 s33, s31, s28
	v_max3_f32 v124, v124, v93, v125
	s_mov_b32 m0, s33
	s_nop 0
	global_load_lds_dwordx4 v241, s[22:23]
	s_add_u32 s22, s35, 0x9b21000
	v_mov_b32_e32 v125, v124
	s_addc_u32 s23, s36, 0
	s_lshl_b32 s33, s34, 1
	v_permlane32_swap_b32_e32 v124, v125
	s_add_i32 s33, s33, s29
	s_mov_b32 m0, s33
	s_nop 0
	global_load_lds_dwordx4 v242, s[22:23]
	s_add_u32 s22, s35, 0x9b21080
	v_max_f32_e32 v124, v124, v125
	s_addc_u32 s23, s36, 0
	s_addk_i32 s33, 0x2000
	s_mov_b32 m0, s33
	s_nop 0
	global_load_lds_dwordx4 v242, s[22:23]
	v_cmp_lt_f32_e32 vcc, s25, v124
	s_cmp_lg_u64 vcc, 0
	v_add_f32_e32 v251, v251, v136
	s_cselect_b64 s[22:23], -1, 0
	s_cbranch_vccnz .LBB0_488

; #define WAIT_BAR(N) asm volatile("s_waitcnt vmcnt(" #N ") lgkmcnt(0)\n\ts_barrier" ::: "memory")
;   #define RESC() do { if constexpr (!NOMAX) if (resc) { asm volatile("s_waitcnt lgkmcnt(0)" ::: "memory"); \
;       _Pragma("unroll") for (int d_ = 0; d_ < 2 * DV2; ++d_) _Pragma("unroll") for (int r = 0; r < 16; ++r) o[d_][r] *= wsf[crow(r, hi)]; } } while (0)
;   #define ROT() do { sl_prev = sl_cur; sl_cur = sl_next; sl_next = (sl_next == (NSLOT - 1) * SLOTB) ? 0 : sl_next + SLOTB; } while (0)
;     ...
;   for (; t + 5 < NT; t += 2) {
;     STEP(pB0, pB1, pA0, pA1, t, true, true, true);     if constexpr (DV2 == 2) { WAIT_BAR(3); } else { WAIT_BAR(2); } RESC(); ROT();
;     STEP(pA0, pA1, pB0, pB1, t + 1, true, true, true); if constexpr (DV2 == 2) { WAIT_BAR(3); } else { WAIT_BAR(2); } RESC(); ROT();
;   }
.LBB0_970:
	v_add_u32_e32 v65, s31, v189
	ds_read_b64_tr_b16 v[178:179], v65 offset:24576
	ds_read_b64_tr_b16 v[180:181], v65 offset:25088
	v_pk_add_f32 v[86:87], v[66:67], v[68:69]
	v_pk_add_f32 v[86:87], v[70:71], v[86:87]
	v_cvt_pk_bf16_f32 v142, v66, v67
	v_cvt_pk_bf16_f32 v143, v68, v69
	v_mfma_f32_32x32x16_bf16 v[98:113], v[82:85], v[158:161], v[32:47]
	ds_read_b64_tr_b16 v[174:175], v65 offset:28672
	ds_read_b64_tr_b16 v[176:177], v65 offset:29184
	v_pk_add_f32 v[66:67], v[72:73], v[86:87]
	v_mfma_f32_32x32x16_bf16 v[82:97], v[166:169], v[158:161], v[32:47]
	v_pk_add_f32 v[130:131], v[74:75], v[66:67]
	v_cvt_pk_bf16_f32 v144, v70, v71
	v_cvt_pk_bf16_f32 v145, v72, v73
	ds_read_b64_tr_b16 v[66:67], v65 offset:25600
	ds_read_b64_tr_b16 v[68:69], v65 offset:26112
	v_pk_add_f32 v[70:71], v[76:77], v[130:131]
	v_pk_add_f32 v[130:131], v[78:79], v[70:71]
	v_cvt_pk_bf16_f32 v138, v74, v75
	v_cvt_pk_bf16_f32 v139, v76, v77
	v_mfma_f32_32x32x16_bf16 v[98:113], v[170:173], v[154:157], v[98:113]
	ds_read_b64_tr_b16 v[70:71], v65 offset:29696
	ds_read_b64_tr_b16 v[72:73], v65 offset:30208
	v_mfma_f32_32x32x16_bf16 v[82:97], v[162:165], v[154:157], v[82:97]
	v_pk_add_f32 v[74:75], v[80:81], v[130:131]
	v_pk_add_f32 v[130:131], v[48:49], v[74:75]
	v_cvt_pk_bf16_f32 v140, v78, v79
	v_cvt_pk_bf16_f32 v141, v80, v81
	ds_read_b64_tr_b16 v[74:75], v65 offset:26624
	ds_read_b64_tr_b16 v[76:77], v65 offset:27136
	v_pk_add_f32 v[78:79], v[50:51], v[130:131]
	v_pk_add_f32 v[78:79], v[52:53], v[78:79]
	v_cvt_pk_bf16_f32 v134, v48, v49
	v_cvt_pk_bf16_f32 v135, v50, v51
	v_mfma_f32_32x32x16_bf16 v[98:113], v[126:129], v[150:153], v[98:113]
	ds_read_b64_tr_b16 v[48:49], v65 offset:30720
	ds_read_b64_tr_b16 v[50:51], v65 offset:31232
	v_mfma_f32_32x32x16_bf16 v[82:97], v[122:125], v[150:153], v[82:97]
	v_pk_add_f32 v[78:79], v[54:55], v[78:79]
	v_pk_add_f32 v[78:79], v[56:57], v[78:79]
	v_cvt_pk_bf16_f32 v136, v52, v53
	v_cvt_pk_bf16_f32 v137, v54, v55
	ds_read_b64_tr_b16 v[52:53], v65 offset:27648
	ds_read_b64_tr_b16 v[54:55], v65 offset:28160
	v_pk_add_f32 v[78:79], v[58:59], v[78:79]
	v_pk_add_f32 v[78:79], v[60:61], v[78:79]
	v_cvt_pk_bf16_f32 v130, v56, v57
	v_cvt_pk_bf16_f32 v131, v58, v59
	v_mfma_f32_32x32x16_bf16 v[98:113], v[118:121], v[146:149], v[98:113]
	ds_read_b64_tr_b16 v[56:57], v65 offset:31744
	ds_read_b64_tr_b16 v[58:59], v65 offset:32256
	v_mfma_f32_32x32x16_bf16 v[82:97], v[114:117], v[146:149], v[82:97]
	v_pk_add_f32 v[78:79], v[62:63], v[78:79]
	v_add_f32_e32 v65, v78, v79
	v_cvt_pk_bf16_f32 v132, v60, v61
	v_cvt_pk_bf16_f32 v133, v62, v63
	v_add_f32_e32 v64, v64, v65
	s_waitcnt lgkmcnt(14)
	v_mfma_f32_32x32x16_bf16 v[0:15], v[142:145], v[178:181], v[0:15]
	s_add_u32 s31, s16, s22
	s_addc_u32 s33, s17, 0
	s_add_i32 m0, s29, s18
	s_add_u32 s34, s31, 0x9ac0800
	s_addc_u32 s35, s33, 0
	global_load_lds_dwordx4 v184, s[34:35]
	v_exp_f32_e32 v98, v98
	v_exp_f32_e32 v99, v99
	v_exp_f32_e32 v100, v100
	v_exp_f32_e32 v101, v101
	s_waitcnt lgkmcnt(12)
	v_mfma_f32_32x32x16_bf16 v[16:31], v[142:145], v[174:177], v[16:31]
	s_add_u32 s34, s20, s22
	s_addc_u32 s35, s21, 0
	s_add_i32 m0, s28, s15
	s_add_u32 s36, s34, 0x9a60a00
	s_addc_u32 s37, s35, 0
	global_load_lds_dwordx4 v185, s[36:37]
	v_exp_f32_e32 v102, v102
	v_exp_f32_e32 v103, v103
	v_exp_f32_e32 v104, v104
	v_exp_f32_e32 v105, v105
	s_waitcnt lgkmcnt(0)
	v_add_u32_e32 v65, s28, v187
	ds_read_b128 v[60:63], v65
	ds_read_b128 v[118:121], v65 offset:512
	v_mfma_f32_32x32x16_bf16 v[0:15], v[138:141], v[66:69], v[0:15]
	v_exp_f32_e32 v106, v106
	v_exp_f32_e32 v107, v107
	v_exp_f32_e32 v108, v108
	v_exp_f32_e32 v109, v109
	ds_read_b128 v[122:125], v65 offset:2048
	ds_read_b128 v[126:129], v65 offset:2560
	v_mfma_f32_32x32x16_bf16 v[16:31], v[138:141], v[70:73], v[16:31]
	v_exp_f32_e32 v110, v110
	v_exp_f32_e32 v111, v111
	v_exp_f32_e32 v112, v112
	v_exp_f32_e32 v113, v113
	ds_read_b128 v[162:165], v65 offset:4096
	ds_read_b128 v[166:169], v65 offset:4608
	v_mfma_f32_32x32x16_bf16 v[0:15], v[134:137], v[74:77], v[0:15]
	v_exp_f32_e32 v82, v82
	v_exp_f32_e32 v83, v83
	v_exp_f32_e32 v84, v84
	v_exp_f32_e32 v85, v85
	ds_read_b128 v[170:173], v65 offset:6144
	ds_read_b128 v[114:117], v65 offset:6656
	v_mfma_f32_32x32x16_bf16 v[16:31], v[134:137], v[48:51], v[16:31]
	v_exp_f32_e32 v86, v86
	v_exp_f32_e32 v87, v87
	v_exp_f32_e32 v88, v88
	v_exp_f32_e32 v89, v89
	v_mfma_f32_32x32x16_bf16 v[0:15], v[130:133], v[52:55], v[0:15]
	v_exp_f32_e32 v90, v90
	v_exp_f32_e32 v91, v91
	v_exp_f32_e32 v92, v92
	v_exp_f32_e32 v93, v93
	v_mfma_f32_32x32x16_bf16 v[16:31], v[130:133], v[56:59], v[16:31]
	v_exp_f32_e32 v94, v94
	v_exp_f32_e32 v95, v95
	v_exp_f32_e32 v96, v96
	v_exp_f32_e32 v97, v97
	s_waitcnt vmcnt(2) lgkmcnt(0)
	s_barrier
; #define WAIT_BAR(N) asm volatile("s_waitcnt vmcnt(" #N ") lgkmcnt(0)\n\ts_barrier" ::: "memory")
;   #define RESC() do { if constexpr (!NOMAX) if (resc) { asm volatile("s_waitcnt lgkmcnt(0)" ::: "memory"); \
;       _Pragma("unroll") for (int d_ = 0; d_ < 2 * DV2; ++d_) _Pragma("unroll") for (int r = 0; r < 16; ++r) o[d_][r] *= wsf[crow(r, hi)]; } } while (0)
;   #define ROT() do { sl_prev = sl_cur; sl_cur = sl_next; sl_next = (sl_next == (NSLOT - 1) * SLOTB) ? 0 : sl_next + SLOTB; } while (0)
;     ...
;   for (; t + 5 < NT; t += 2) {
;     STEP(pB0, pB1, pA0, pA1, t, true, true, true);     if constexpr (DV2 == 2) { WAIT_BAR(3); } else { WAIT_BAR(2); } RESC(); ROT();
;     STEP(pA0, pA1, pB0, pB1, t + 1, true, true, true); if constexpr (DV2 == 2) { WAIT_BAR(3); } else { WAIT_BAR(2); } RESC(); ROT();
;   }
	s_add_i32 s30, s28, 0x2000
	s_cmpk_lg_i32 s28, 0x4000
	s_cselect_b32 s30, s30, 0
	v_add_u32_e32 v65, s29, v189
	ds_read_b64_tr_b16 v[174:175], v65 offset:24576
	ds_read_b64_tr_b16 v[176:177], v65 offset:25088
	v_mfma_f32_32x32x16_bf16 v[66:81], v[60:63], v[158:161], v[32:47]
	v_pk_add_f32 v[48:49], v[98:99], v[100:101]
	v_pk_add_f32 v[48:49], v[102:103], v[48:49]
	v_cvt_pk_bf16_f32 v142, v98, v99
	v_cvt_pk_bf16_f32 v143, v100, v101
	ds_read_b64_tr_b16 v[178:179], v65 offset:28672
	ds_read_b64_tr_b16 v[180:181], v65 offset:29184
	v_pk_add_f32 v[48:49], v[104:105], v[48:49]
	v_pk_add_f32 v[130:131], v[106:107], v[48:49]
	v_mfma_f32_32x32x16_bf16 v[48:63], v[118:121], v[158:161], v[32:47]
	v_cvt_pk_bf16_f32 v144, v102, v103
	v_cvt_pk_bf16_f32 v145, v104, v105
	ds_read_b64_tr_b16 v[98:99], v65 offset:25600
	ds_read_b64_tr_b16 v[100:101], v65 offset:26112
	v_mfma_f32_32x32x16_bf16 v[66:81], v[122:125], v[154:157], v[66:81]
	v_pk_add_f32 v[102:103], v[108:109], v[130:131]
	v_pk_add_f32 v[118:119], v[110:111], v[102:103]
	v_cvt_pk_bf16_f32 v138, v106, v107
	v_cvt_pk_bf16_f32 v139, v108, v109
	ds_read_b64_tr_b16 v[102:103], v65 offset:29696
	ds_read_b64_tr_b16 v[104:105], v65 offset:30208
	v_mfma_f32_32x32x16_bf16 v[48:63], v[126:129], v[154:157], v[48:63]
	v_pk_add_f32 v[106:107], v[112:113], v[118:119]
	v_pk_add_f32 v[118:119], v[82:83], v[106:107]
	v_cvt_pk_bf16_f32 v140, v110, v111
	v_cvt_pk_bf16_f32 v141, v112, v113
	ds_read_b64_tr_b16 v[106:107], v65 offset:26624
	ds_read_b64_tr_b16 v[108:109], v65 offset:27136
	v_mfma_f32_32x32x16_bf16 v[66:81], v[162:165], v[150:153], v[66:81]
	v_pk_add_f32 v[110:111], v[84:85], v[118:119]
	v_pk_add_f32 v[118:119], v[86:87], v[110:111]
	v_cvt_pk_bf16_f32 v134, v82, v83
	v_cvt_pk_bf16_f32 v135, v84, v85
	ds_read_b64_tr_b16 v[110:111], v65 offset:30720
	ds_read_b64_tr_b16 v[112:113], v65 offset:31232
	v_mfma_f32_32x32x16_bf16 v[48:63], v[166:169], v[150:153], v[48:63]
	v_pk_add_f32 v[82:83], v[88:89], v[118:119]
	v_pk_add_f32 v[82:83], v[90:91], v[82:83]
	v_cvt_pk_bf16_f32 v136, v86, v87
	v_cvt_pk_bf16_f32 v137, v88, v89
	ds_read_b64_tr_b16 v[86:87], v65 offset:27648
	ds_read_b64_tr_b16 v[88:89], v65 offset:28160
	v_mfma_f32_32x32x16_bf16 v[66:81], v[170:173], v[146:149], v[66:81]
	v_pk_add_f32 v[82:83], v[92:93], v[82:83]
	v_pk_add_f32 v[82:83], v[94:95], v[82:83]
	v_cvt_pk_bf16_f32 v130, v90, v91
	v_cvt_pk_bf16_f32 v131, v92, v93
	ds_read_b64_tr_b16 v[90:91], v65 offset:31744
	ds_read_b64_tr_b16 v[92:93], v65 offset:32256
	v_mfma_f32_32x32x16_bf16 v[48:63], v[114:117], v[146:149], v[48:63]
	v_pk_add_f32 v[82:83], v[96:97], v[82:83]
	v_add_f32_e32 v65, v82, v83
	v_cvt_pk_bf16_f32 v132, v94, v95
	v_cvt_pk_bf16_f32 v133, v96, v97
	v_add_f32_e32 v64, v64, v65
	s_waitcnt lgkmcnt(14)
	v_mfma_f32_32x32x16_bf16 v[0:15], v[142:145], v[174:177], v[0:15]
	s_add_i32 m0, s28, s18
	s_add_u32 s36, s31, 0x9af0800
	s_addc_u32 s37, s33, 0
	global_load_lds_dwordx4 v184, s[36:37]
	v_exp_f32_e32 v66, v66
	v_exp_f32_e32 v67, v67
	v_exp_f32_e32 v68, v68
	v_exp_f32_e32 v69, v69
	s_waitcnt lgkmcnt(12)
	v_mfma_f32_32x32x16_bf16 v[16:31], v[142:145], v[178:181], v[16:31]
	s_add_i32 m0, s30, s15
	s_add_u32 s34, s34, 0x9a90a00
	s_addc_u32 s35, s35, 0
	global_load_lds_dwordx4 v185, s[34:35]
	v_exp_f32_e32 v70, v70
	v_exp_f32_e32 v71, v71
	v_exp_f32_e32 v72, v72
	v_exp_f32_e32 v73, v73
	v_add_u32_e32 v65, s30, v187
	ds_read_b128 v[82:85], v65
	ds_read_b128 v[166:169], v65 offset:512
	v_mfma_f32_32x32x16_bf16 v[0:15], v[138:141], v[98:101], v[0:15]
	v_exp_f32_e32 v74, v74
	s_waitcnt lgkmcnt(0)
	v_exp_f32_e32 v75, v75
	v_exp_f32_e32 v76, v76
	v_exp_f32_e32 v77, v77
	ds_read_b128 v[170:173], v65 offset:2048
	ds_read_b128 v[162:165], v65 offset:2560
	v_mfma_f32_32x32x16_bf16 v[16:31], v[138:141], v[102:105], v[16:31]
	v_exp_f32_e32 v78, v78
	v_exp_f32_e32 v79, v79
	v_exp_f32_e32 v80, v80
	v_exp_f32_e32 v81, v81
	ds_read_b128 v[126:129], v65 offset:4096
	ds_read_b128 v[122:125], v65 offset:4608
	v_mfma_f32_32x32x16_bf16 v[0:15], v[134:137], v[106:109], v[0:15]
	v_exp_f32_e32 v48, v48
	v_exp_f32_e32 v49, v49
	v_exp_f32_e32 v50, v50
	v_exp_f32_e32 v51, v51
	ds_read_b128 v[118:121], v65 offset:6144
	ds_read_b128 v[114:117], v65 offset:6656
	v_mfma_f32_32x32x16_bf16 v[16:31], v[134:137], v[110:113], v[16:31]
	v_exp_f32_e32 v52, v52
	v_exp_f32_e32 v53, v53
	v_exp_f32_e32 v54, v54
	v_exp_f32_e32 v55, v55
	v_mfma_f32_32x32x16_bf16 v[0:15], v[130:133], v[86:89], v[0:15]
	v_exp_f32_e32 v56, v56
	v_exp_f32_e32 v57, v57
	v_exp_f32_e32 v58, v58
	v_exp_f32_e32 v59, v59
	v_mfma_f32_32x32x16_bf16 v[16:31], v[130:133], v[90:93], v[16:31]
	v_exp_f32_e32 v60, v60
	v_exp_f32_e32 v61, v61
	v_exp_f32_e32 v62, v62
	v_exp_f32_e32 v63, v63
	s_add_i32 s33, s30, 0x2000
	s_cmpk_lg_i32 s30, 0x4000
	s_mov_b32 s31, s28
	s_cselect_b32 s28, s33, 0
	s_add_i32 s24, s24, 2
	s_add_u32 s20, s20, 0x60000
	s_addc_u32 s21, s21, 0
	s_waitcnt vmcnt(2) lgkmcnt(0)
	s_barrier
	s_add_u32 s16, s16, 0x60000
	s_addc_u32 s17, s17, 0
	s_mov_b32 s29, s30
	s_cmp_gt_u32 s24, 56
	s_cbranch_scc0 .LBB0_970
;   #define RESC() do { if constexpr (!NOMAX) if (resc) { asm volatile("s_waitcnt lgkmcnt(0)" ::: "memory"); \
;       _Pragma("unroll") for (int d_ = 0; d_ < 2 * DV2; ++d_) _Pragma("unroll") for (int r = 0; r < 16; ++r) o[d_][r] *= wsf[crow(r, hi)]; } } while (0)
;   #define ROT() do { sl_prev = sl_cur; sl_cur = sl_next; sl_next = (sl_next == (NSLOT - 1) * SLOTB) ? 0 : sl_next + SLOTB; } while (0)
;   #define ENDW(tt) do { if constexpr (DV2 == 2) { if ((tt) + 3 < NT) { WAIT_BAR(3); } else if ((tt) + 2 < NT) { WAIT_BAR(2); } else { WAIT_BAR(0); } } \
;     else { if ((tt) + 3 < NT) { WAIT_BAR(2); } else if ((tt) + 2 < NT) { WAIT_BAR(1); } else { WAIT_BAR(0); } } } while (0)
;     ...
;   for (; t + 1 < NT; t += 2) {
;     STEP(pB0, pB1, pA0, pA1, t, (t + 3 < NT), (t + 1 < NT), (t + 1 < NT));         ENDW(t);     RESC(); ROT();
;     STEP(pA0, pA1, pB0, pB1, t + 1, (t + 4 < NT), (t + 2 < NT), (t + 2 < NT));     ENDW(t + 1); RESC(); ROT();
;   }
;   STEP(pB0, pB1, pA0, pA1, NT - 1, false, false, false); RESC();
	s_and_b32 s16, s23, 0x3fffffc0
	s_lshl_b32 s16, s16, 2
	s_add_i32 s16, s16, 0
	ds_read_b64_tr_b16 v[174:175], v189 offset:32768
	ds_read_b64_tr_b16 v[176:177], v189 offset:33280
	v_add_f32_e32 v65, v66, v67
	v_add_f32_e32 v65, v68, v65
	v_add_f32_e32 v65, v69, v65
	v_add_f32_e32 v65, v70, v65
	v_add_f32_e32 v65, v71, v65
	v_cvt_pk_bf16_f32 v142, v66, v67
	v_cvt_pk_bf16_f32 v143, v68, v69
	s_waitcnt lgkmcnt(9)
	v_mfma_f32_32x32x16_bf16 v[98:113], v[82:85], v[158:161], v[32:47]
	ds_read_b64_tr_b16 v[178:179], v189 offset:36864
	ds_read_b64_tr_b16 v[180:181], v189 offset:37376
	v_add_f32_e32 v65, v72, v65
	v_add_f32_e32 v65, v73, v65
	v_add_f32_e32 v65, v74, v65
	v_add_f32_e32 v65, v75, v65
	v_cvt_pk_bf16_f32 v144, v70, v71
	v_cvt_pk_bf16_f32 v145, v72, v73
	s_waitcnt lgkmcnt(10)
	v_mfma_f32_32x32x16_bf16 v[82:97], v[166:169], v[158:161], v[32:47]
	ds_read_b64_tr_b16 v[66:67], v189 offset:33792
	ds_read_b64_tr_b16 v[68:69], v189 offset:34304
	v_add_f32_e32 v65, v76, v65
	v_add_f32_e32 v65, v77, v65
	v_add_f32_e32 v65, v78, v65
	v_add_f32_e32 v65, v79, v65
	v_cvt_pk_bf16_f32 v138, v74, v75
	v_cvt_pk_bf16_f32 v139, v76, v77
	s_waitcnt lgkmcnt(11)
	v_mfma_f32_32x32x16_bf16 v[98:113], v[170:173], v[154:157], v[98:113]
	ds_read_b64_tr_b16 v[70:71], v189 offset:37888
	ds_read_b64_tr_b16 v[72:73], v189 offset:38400
	v_add_f32_e32 v65, v80, v65
	v_add_f32_e32 v65, v81, v65
	v_add_f32_e32 v65, v48, v65
	v_add_f32_e32 v65, v49, v65
	v_cvt_pk_bf16_f32 v140, v78, v79
	v_cvt_pk_bf16_f32 v141, v80, v81
	s_waitcnt lgkmcnt(12)
	v_mfma_f32_32x32x16_bf16 v[82:97], v[162:165], v[154:157], v[82:97]
	ds_read_b64_tr_b16 v[74:75], v189 offset:34816
	ds_read_b64_tr_b16 v[76:77], v189 offset:35328
	v_add_f32_e32 v65, v50, v65
	v_add_f32_e32 v65, v51, v65
	v_add_f32_e32 v65, v52, v65
	v_add_f32_e32 v65, v53, v65
	v_cvt_pk_bf16_f32 v134, v48, v49
	v_cvt_pk_bf16_f32 v135, v50, v51
	s_waitcnt lgkmcnt(13)
	v_mfma_f32_32x32x16_bf16 v[98:113], v[126:129], v[150:153], v[98:113]
	ds_read_b64_tr_b16 v[48:49], v189 offset:38912
	ds_read_b64_tr_b16 v[50:51], v189 offset:39424
	v_add_f32_e32 v65, v54, v65
	v_add_f32_e32 v65, v55, v65
	v_add_f32_e32 v65, v56, v65
	v_add_f32_e32 v65, v57, v65
	v_cvt_pk_bf16_f32 v136, v52, v53
	v_cvt_pk_bf16_f32 v137, v54, v55
	s_waitcnt lgkmcnt(14)
	v_mfma_f32_32x32x16_bf16 v[82:97], v[122:125], v[150:153], v[82:97]
	ds_read_b64_tr_b16 v[52:53], v189 offset:35840
	ds_read_b64_tr_b16 v[54:55], v189 offset:36352
	v_add_f32_e32 v65, v58, v65
	v_add_f32_e32 v65, v59, v65
	v_add_f32_e32 v65, v60, v65
	v_add_f32_e32 v65, v61, v65
	v_cvt_pk_bf16_f32 v130, v56, v57
	v_cvt_pk_bf16_f32 v131, v58, v59
	s_waitcnt lgkmcnt(14)
	v_mfma_f32_32x32x16_bf16 v[98:113], v[118:121], v[146:149], v[98:113]
	ds_read_b64_tr_b16 v[56:57], v189 offset:39936
	ds_read_b64_tr_b16 v[58:59], v189 offset:40448
	v_add_f32_e32 v65, v62, v65
	v_add_f32_e32 v65, v63, v65
	v_add_f32_e32 v65, 0, v65
	v_cvt_pk_bf16_f32 v132, v60, v61
	v_cvt_pk_bf16_f32 v133, v62, v63
	v_mfma_f32_32x32x16_bf16 v[82:97], v[114:117], v[146:149], v[82:97]
	s_add_u32 s20, s10, 0xba0000
	s_addc_u32 s21, s11, 0
	s_cmp_lg_u32 0, -1
	s_cselect_b32 s17, 0, 0
	s_add_i32 s17, s17, s19
	s_add_i32 s19, s17, 0x4000
	s_mov_b32 s22, m0
	s_mov_b32 m0, s19
	s_nop 0
	global_load_lds_dwordx4 v184, s[20:21]
	s_mov_b32 m0, s22
	s_add_u32 s20, s8, 0xb40000
	s_addc_u32 s21, s9, 0
	s_mov_b32 s19, m0
	s_mov_b32 m0, s15
	s_nop 0
	global_load_lds_dwordx4 v185, s[20:21]
	s_mov_b32 m0, s19
	v_add_f32_e32 v183, v64, v65
	s_waitcnt lgkmcnt(14)
	v_mfma_f32_32x32x16_bf16 v[0:15], v[142:145], v[174:177], v[0:15]
	v_exp_f32_e32 v98, v98
	v_exp_f32_e32 v99, v99
	v_exp_f32_e32 v100, v100
	v_exp_f32_e32 v101, v101
	s_waitcnt lgkmcnt(12)
	v_mfma_f32_32x32x16_bf16 v[16:31], v[142:145], v[178:181], v[16:31]
	v_exp_f32_e32 v102, v102
	v_exp_f32_e32 v103, v103
	v_exp_f32_e32 v104, v104
	v_exp_f32_e32 v105, v105
	ds_read_b128 v[60:63], v187
	ds_read_b128 v[78:81], v187 offset:512
	s_waitcnt lgkmcnt(12)
	v_mfma_f32_32x32x16_bf16 v[0:15], v[138:141], v[66:69], v[0:15]
	v_exp_f32_e32 v106, v106
	v_exp_f32_e32 v107, v107
	v_exp_f32_e32 v108, v108
	v_exp_f32_e32 v109, v109
	ds_read_b128 v[162:165], v187 offset:2048
	ds_read_b128 v[166:169], v187 offset:2560
	s_waitcnt lgkmcnt(12)
	v_mfma_f32_32x32x16_bf16 v[16:31], v[138:141], v[70:73], v[16:31]
	v_exp_f32_e32 v110, v110
	v_exp_f32_e32 v111, v111
	v_exp_f32_e32 v112, v112
	v_exp_f32_e32 v113, v113
	ds_read_b128 v[68:71], v187 offset:4096
	ds_read_b128 v[170:173], v187 offset:4608
	s_waitcnt lgkmcnt(12)
	v_mfma_f32_32x32x16_bf16 v[0:15], v[134:137], v[74:77], v[0:15]
	v_exp_f32_e32 v82, v82
	v_exp_f32_e32 v83, v83
	v_exp_f32_e32 v84, v84
	v_exp_f32_e32 v85, v85
	ds_read_b128 v[72:75], v187 offset:6144
	ds_read_b128 v[64:67], v187 offset:6656
	s_waitcnt lgkmcnt(12)
	v_mfma_f32_32x32x16_bf16 v[16:31], v[134:137], v[48:51], v[16:31]
	v_exp_f32_e32 v86, v86
	v_exp_f32_e32 v87, v87
	v_exp_f32_e32 v88, v88
	v_exp_f32_e32 v89, v89
	s_waitcnt lgkmcnt(10)
	v_mfma_f32_32x32x16_bf16 v[0:15], v[130:133], v[52:55], v[0:15]
	v_exp_f32_e32 v90, v90
	v_exp_f32_e32 v91, v91
	v_exp_f32_e32 v92, v92
	v_exp_f32_e32 v93, v93
	s_waitcnt lgkmcnt(8)
	v_mfma_f32_32x32x16_bf16 v[16:31], v[130:133], v[56:59], v[16:31]
	v_exp_f32_e32 v94, v94
	v_exp_f32_e32 v95, v95
	v_exp_f32_e32 v96, v96
	v_exp_f32_e32 v97, v97
	s_waitcnt vmcnt(2) lgkmcnt(0)
	s_barrier
;   #define RESC() do { if constexpr (!NOMAX) if (resc) { asm volatile("s_waitcnt lgkmcnt(0)" ::: "memory"); \
;       _Pragma("unroll") for (int d_ = 0; d_ < 2 * DV2; ++d_) _Pragma("unroll") for (int r = 0; r < 16; ++r) o[d_][r] *= wsf[crow(r, hi)]; } } while (0)
;   #define ROT() do { sl_prev = sl_cur; sl_cur = sl_next; sl_next = (sl_next == (NSLOT - 1) * SLOTB) ? 0 : sl_next + SLOTB; } while (0)
;   #define ENDW(tt) do { if constexpr (DV2 == 2) { if ((tt) + 3 < NT) { WAIT_BAR(3); } else if ((tt) + 2 < NT) { WAIT_BAR(2); } else { WAIT_BAR(0); } } \
;     else { if ((tt) + 3 < NT) { WAIT_BAR(2); } else if ((tt) + 2 < NT) { WAIT_BAR(1); } else { WAIT_BAR(0); } } } while (0)
;     ...
;   for (; t + 1 < NT; t += 2) {
;     STEP(pB0, pB1, pA0, pA1, t, (t + 3 < NT), (t + 1 < NT), (t + 1 < NT));         ENDW(t);     RESC(); ROT();
;     STEP(pA0, pA1, pB0, pB1, t + 1, (t + 4 < NT), (t + 2 < NT), (t + 2 < NT));     ENDW(t + 1); RESC(); ROT();
;   }
;   STEP(pB0, pB1, pA0, pA1, NT - 1, false, false, false); RESC();
	ds_read_b64_tr_b16 v[174:175], v189 offset:40960
	ds_read_b64_tr_b16 v[176:177], v189 offset:41472
	v_add_f32_e32 v48, v98, v99
	v_add_f32_e32 v48, v100, v48
	v_add_f32_e32 v48, v101, v48
	v_add_f32_e32 v48, v102, v48
	v_add_f32_e32 v48, v103, v48
	v_cvt_pk_bf16_f32 v142, v98, v99
	v_cvt_pk_bf16_f32 v143, v100, v101
	s_waitcnt lgkmcnt(9)
	v_mfma_f32_32x32x16_bf16 v[114:129], v[60:63], v[158:161], v[32:47]
	ds_read_b64_tr_b16 v[98:99], v189 offset:45056
	ds_read_b64_tr_b16 v[100:101], v189 offset:45568
	v_add_f32_e32 v48, v104, v48
	v_add_f32_e32 v48, v105, v48
	v_add_f32_e32 v48, v106, v48
	v_add_f32_e32 v130, v107, v48
	s_waitcnt lgkmcnt(10)
	v_mfma_f32_32x32x16_bf16 v[48:63], v[78:81], v[158:161], v[32:47]
	v_cvt_pk_bf16_f32 v144, v102, v103
	v_cvt_pk_bf16_f32 v145, v104, v105
	ds_read_b64_tr_b16 v[76:77], v189 offset:41984
	ds_read_b64_tr_b16 v[78:79], v189 offset:42496
	v_add_f32_e32 v80, v108, v130
	v_add_f32_e32 v80, v109, v80
	v_add_f32_e32 v80, v110, v80
	v_add_f32_e32 v80, v111, v80
	v_cvt_pk_bf16_f32 v138, v106, v107
	v_cvt_pk_bf16_f32 v139, v108, v109
	s_waitcnt lgkmcnt(11)
	v_mfma_f32_32x32x16_bf16 v[114:129], v[162:165], v[154:157], v[114:129]
	ds_read_b64_tr_b16 v[102:103], v189 offset:46080
	ds_read_b64_tr_b16 v[104:105], v189 offset:46592
	s_waitcnt lgkmcnt(12)
	v_mfma_f32_32x32x16_bf16 v[48:63], v[166:169], v[154:157], v[48:63]
	v_add_f32_e32 v80, v112, v80
	v_add_f32_e32 v80, v113, v80
	v_add_f32_e32 v80, v82, v80
	v_add_f32_e32 v80, v83, v80
	v_cvt_pk_bf16_f32 v140, v110, v111
	v_cvt_pk_bf16_f32 v141, v112, v113
	ds_read_b64_tr_b16 v[106:107], v189 offset:43008
	ds_read_b64_tr_b16 v[108:109], v189 offset:43520
	s_waitcnt lgkmcnt(13)
	v_mfma_f32_32x32x16_bf16 v[114:129], v[68:71], v[150:153], v[114:129]
	v_add_f32_e32 v68, v84, v80
	v_add_f32_e32 v68, v85, v68
	v_add_f32_e32 v68, v86, v68
	v_add_f32_e32 v80, v87, v68
	v_cvt_pk_bf16_f32 v134, v82, v83
	v_cvt_pk_bf16_f32 v135, v84, v85
	ds_read_b64_tr_b16 v[68:69], v189 offset:47104
	ds_read_b64_tr_b16 v[70:71], v189 offset:47616
	s_waitcnt lgkmcnt(14)
	v_mfma_f32_32x32x16_bf16 v[48:63], v[170:173], v[150:153], v[48:63]
	v_add_f32_e32 v80, v88, v80
	v_add_f32_e32 v80, v89, v80
	v_add_f32_e32 v80, v90, v80
	v_add_f32_e32 v80, v91, v80
	v_cvt_pk_bf16_f32 v136, v86, v87
	v_cvt_pk_bf16_f32 v137, v88, v89
	ds_read_b64_tr_b16 v[84:85], v189 offset:44032
	ds_read_b64_tr_b16 v[86:87], v189 offset:44544
	s_waitcnt lgkmcnt(14)
	v_mfma_f32_32x32x16_bf16 v[114:129], v[72:75], v[146:149], v[114:129]
	v_add_f32_e32 v72, v92, v80
	v_add_f32_e32 v72, v93, v72
	v_add_f32_e32 v72, v94, v72
	v_add_f32_e32 v80, v95, v72
	v_cvt_pk_bf16_f32 v130, v90, v91
	v_cvt_pk_bf16_f32 v131, v92, v93
	ds_read_b64_tr_b16 v[72:73], v189 offset:48128
	ds_read_b64_tr_b16 v[74:75], v189 offset:48640
	v_mfma_f32_32x32x16_bf16 v[48:63], v[64:67], v[146:149], v[48:63]
	v_add_f32_e32 v64, v96, v80
	v_add_f32_e32 v64, v97, v64
	v_add_f32_e32 v64, 0, v64
	v_cvt_pk_bf16_f32 v132, v94, v95
	v_cvt_pk_bf16_f32 v133, v96, v97
	s_add_u32 s10, s10, 0xbd0000
	s_addc_u32 s11, s11, 0
	s_mov_b32 s19, m0
	s_mov_b32 m0, s18
	s_nop 0
	global_load_lds_dwordx4 v184, s[10:11]
	s_mov_b32 m0, s19
	s_add_u32 s10, s8, 0xb70000
	s_addc_u32 s11, s9, 0
	s_add_i32 s18, s17, 0x8000
	s_mov_b32 s19, m0
	s_mov_b32 m0, s18
	s_nop 0
	global_load_lds_dwordx4 v185, s[10:11]
	s_mov_b32 m0, s19
	v_add_f32_e32 v178, v183, v64
	s_waitcnt lgkmcnt(14)
	v_mfma_f32_32x32x16_bf16 v[0:15], v[142:145], v[174:177], v[0:15]
	v_exp_f32_e32 v114, v114
	v_exp_f32_e32 v115, v115
	v_exp_f32_e32 v116, v116
	v_exp_f32_e32 v117, v117
	s_waitcnt lgkmcnt(12)
	v_mfma_f32_32x32x16_bf16 v[16:31], v[142:145], v[98:101], v[16:31]
	v_exp_f32_e32 v118, v118
	v_exp_f32_e32 v119, v119
	v_exp_f32_e32 v120, v120
	v_exp_f32_e32 v121, v121
	ds_read_b128 v[64:67], v187 offset:8192
	ds_read_b128 v[88:91], v187 offset:8704
	s_waitcnt lgkmcnt(12)
	v_mfma_f32_32x32x16_bf16 v[0:15], v[138:141], v[76:79], v[0:15]
	v_exp_f32_e32 v122, v122
	v_exp_f32_e32 v123, v123
	v_exp_f32_e32 v124, v124
	v_exp_f32_e32 v125, v125
	ds_read_b128 v[92:95], v187 offset:10240
	ds_read_b128 v[162:165], v187 offset:10752
	s_waitcnt lgkmcnt(12)
	v_mfma_f32_32x32x16_bf16 v[16:31], v[138:141], v[102:105], v[16:31]
	v_exp_f32_e32 v126, v126
	v_exp_f32_e32 v127, v127
	v_exp_f32_e32 v128, v128
	v_exp_f32_e32 v129, v129
	ds_read_b128 v[166:169], v187 offset:12288
	ds_read_b128 v[170:173], v187 offset:12800
	s_waitcnt lgkmcnt(12)
	v_mfma_f32_32x32x16_bf16 v[0:15], v[134:137], v[106:109], v[0:15]
	v_exp_f32_e32 v48, v48
	v_exp_f32_e32 v49, v49
	v_exp_f32_e32 v50, v50
	v_exp_f32_e32 v51, v51
	ds_read_b128 v[174:177], v187 offset:14336
	ds_read_b128 v[80:83], v187 offset:14848
	s_waitcnt lgkmcnt(12)
	v_mfma_f32_32x32x16_bf16 v[16:31], v[134:137], v[68:71], v[16:31]
	v_exp_f32_e32 v52, v52
	v_exp_f32_e32 v53, v53
	v_exp_f32_e32 v54, v54
	v_exp_f32_e32 v55, v55
	s_waitcnt lgkmcnt(10)
	v_mfma_f32_32x32x16_bf16 v[0:15], v[130:133], v[84:87], v[0:15]
	v_exp_f32_e32 v56, v56
	v_exp_f32_e32 v57, v57
	v_exp_f32_e32 v58, v58
	v_exp_f32_e32 v59, v59
	s_waitcnt lgkmcnt(8)
	v_mfma_f32_32x32x16_bf16 v[16:31], v[130:133], v[72:75], v[16:31]
	v_exp_f32_e32 v60, v60
	v_exp_f32_e32 v61, v61
	v_exp_f32_e32 v62, v62
	v_exp_f32_e32 v63, v63
	s_waitcnt vmcnt(2) lgkmcnt(0)
	s_barrier
;   #define RESC() do { if constexpr (!NOMAX) if (resc) { asm volatile("s_waitcnt lgkmcnt(0)" ::: "memory"); \
;       _Pragma("unroll") for (int d_ = 0; d_ < 2 * DV2; ++d_) _Pragma("unroll") for (int r = 0; r < 16; ++r) o[d_][r] *= wsf[crow(r, hi)]; } } while (0)
;   #define ROT() do { sl_prev = sl_cur; sl_cur = sl_next; sl_next = (sl_next == (NSLOT - 1) * SLOTB) ? 0 : sl_next + SLOTB; } while (0)
;   #define ENDW(tt) do { if constexpr (DV2 == 2) { if ((tt) + 3 < NT) { WAIT_BAR(3); } else if ((tt) + 2 < NT) { WAIT_BAR(2); } else { WAIT_BAR(0); } } \
;     else { if ((tt) + 3 < NT) { WAIT_BAR(2); } else if ((tt) + 2 < NT) { WAIT_BAR(1); } else { WAIT_BAR(0); } } } while (0)
;     ...
;   for (; t + 1 < NT; t += 2) {
;     STEP(pB0, pB1, pA0, pA1, t, (t + 3 < NT), (t + 1 < NT), (t + 1 < NT));         ENDW(t);     RESC(); ROT();
;     STEP(pA0, pA1, pB0, pB1, t + 1, (t + 4 < NT), (t + 2 < NT), (t + 2 < NT));     ENDW(t + 1); RESC(); ROT();
;   }
;   STEP(pB0, pB1, pA0, pA1, NT - 1, false, false, false); RESC();
	ds_read_b64_tr_b16 v[84:85], v189 offset:24576
	ds_read_b64_tr_b16 v[86:87], v189 offset:25088
	v_add_f32_e32 v68, v114, v115
	v_add_f32_e32 v68, v116, v68
	v_add_f32_e32 v68, v117, v68
	v_add_f32_e32 v68, v118, v68
	v_add_f32_e32 v68, v119, v68
	v_cvt_pk_bf16_f32 v142, v114, v115
	v_cvt_pk_bf16_f32 v143, v116, v117
	s_waitcnt lgkmcnt(9)
	v_mfma_f32_32x32x16_bf16 v[96:111], v[64:67], v[158:161], v[32:47]
	ds_read_b64_tr_b16 v[112:113], v189 offset:28672
	ds_read_b64_tr_b16 v[114:115], v189 offset:29184
	v_add_f32_e32 v64, v120, v68
	v_add_f32_e32 v64, v121, v64
	v_add_f32_e32 v64, v122, v64
	v_add_f32_e32 v116, v123, v64
	v_cvt_pk_bf16_f32 v144, v118, v119
	v_cvt_pk_bf16_f32 v145, v120, v121
	s_waitcnt lgkmcnt(10)
	v_mfma_f32_32x32x16_bf16 v[64:79], v[88:91], v[158:161], v[32:47]
	ds_read_b64_tr_b16 v[88:89], v189 offset:25600
	ds_read_b64_tr_b16 v[90:91], v189 offset:26112
	s_waitcnt lgkmcnt(11)
	v_mfma_f32_32x32x16_bf16 v[96:111], v[92:95], v[154:157], v[96:111]
	v_add_f32_e32 v92, v124, v116
	v_add_f32_e32 v92, v125, v92
	v_add_f32_e32 v92, v126, v92
	v_add_f32_e32 v116, v127, v92
	v_cvt_pk_bf16_f32 v138, v122, v123
	v_cvt_pk_bf16_f32 v139, v124, v125
	ds_read_b64_tr_b16 v[92:93], v189 offset:29696
	ds_read_b64_tr_b16 v[94:95], v189 offset:30208
	v_add_f32_e32 v116, v128, v116
	v_add_f32_e32 v116, v129, v116
	v_add_f32_e32 v116, v48, v116
	v_add_f32_e32 v120, v49, v116
	v_cvt_pk_bf16_f32 v140, v126, v127
	v_cvt_pk_bf16_f32 v141, v128, v129
	s_waitcnt lgkmcnt(12)
	v_mfma_f32_32x32x16_bf16 v[64:79], v[162:165], v[154:157], v[64:79]
	ds_read_b64_tr_b16 v[116:117], v189 offset:26624
	ds_read_b64_tr_b16 v[118:119], v189 offset:27136
	v_add_f32_e32 v120, v50, v120
	v_add_f32_e32 v120, v51, v120
	v_add_f32_e32 v120, v52, v120
	v_add_f32_e32 v120, v53, v120
	v_cvt_pk_bf16_f32 v134, v48, v49
	v_cvt_pk_bf16_f32 v135, v50, v51
	s_waitcnt lgkmcnt(13)
	v_mfma_f32_32x32x16_bf16 v[96:111], v[166:169], v[150:153], v[96:111]
	ds_read_b64_tr_b16 v[48:49], v189 offset:30720
	ds_read_b64_tr_b16 v[50:51], v189 offset:31232
	v_add_f32_e32 v120, v54, v120
	v_add_f32_e32 v120, v55, v120
	v_add_f32_e32 v120, v56, v120
	v_add_f32_e32 v120, v57, v120
	v_cvt_pk_bf16_f32 v136, v52, v53
	v_cvt_pk_bf16_f32 v137, v54, v55
	s_waitcnt lgkmcnt(14)
	v_mfma_f32_32x32x16_bf16 v[64:79], v[170:173], v[150:153], v[64:79]
	ds_read_b64_tr_b16 v[52:53], v189 offset:27648
	ds_read_b64_tr_b16 v[54:55], v189 offset:28160
	v_add_f32_e32 v120, v58, v120
	v_add_f32_e32 v120, v59, v120
	v_add_f32_e32 v120, v60, v120
	v_add_f32_e32 v120, v61, v120
	v_cvt_pk_bf16_f32 v130, v56, v57
	v_cvt_pk_bf16_f32 v131, v58, v59
	s_waitcnt lgkmcnt(14)
	v_mfma_f32_32x32x16_bf16 v[96:111], v[174:177], v[146:149], v[96:111]
	ds_read_b64_tr_b16 v[56:57], v189 offset:31744
	ds_read_b64_tr_b16 v[58:59], v189 offset:32256
	v_mfma_f32_32x32x16_bf16 v[64:79], v[80:83], v[146:149], v[64:79]
	v_add_f32_e32 v80, v62, v120
	v_add_f32_e32 v80, v63, v80
	v_add_f32_e32 v80, 0, v80
	v_cvt_pk_bf16_f32 v132, v60, v61
	v_cvt_pk_bf16_f32 v133, v62, v63
	s_add_u32 s10, s8, 0xba0000
	s_addc_u32 s11, s9, 0
	s_add_i32 s17, s17, 0xa000
	s_mov_b32 s18, m0
	s_mov_b32 m0, s17
	s_nop 0
	global_load_lds_dwordx4 v185, s[10:11]
	s_mov_b32 m0, s18
	v_add_f32_e32 v128, v178, v80
	s_waitcnt lgkmcnt(14)
	v_mfma_f32_32x32x16_bf16 v[0:15], v[142:145], v[84:87], v[0:15]
	v_exp_f32_e32 v96, v96
	v_exp_f32_e32 v97, v97
	v_exp_f32_e32 v98, v98
	v_exp_f32_e32 v99, v99
	s_waitcnt lgkmcnt(12)
	v_mfma_f32_32x32x16_bf16 v[16:31], v[142:145], v[112:115], v[16:31]
	v_exp_f32_e32 v100, v100
	v_exp_f32_e32 v101, v101
	v_exp_f32_e32 v102, v102
	v_exp_f32_e32 v103, v103
	ds_read_b128 v[60:63], v187 offset:16384
	ds_read_b128 v[120:123], v187 offset:16896
	s_waitcnt lgkmcnt(12)
	v_mfma_f32_32x32x16_bf16 v[0:15], v[138:141], v[88:91], v[0:15]
	v_exp_f32_e32 v104, v104
	v_exp_f32_e32 v105, v105
	v_exp_f32_e32 v106, v106
	v_exp_f32_e32 v107, v107
	ds_read_b128 v[124:127], v187 offset:18432
	ds_read_b128 v[162:165], v187 offset:18944
	s_waitcnt lgkmcnt(12)
	v_mfma_f32_32x32x16_bf16 v[16:31], v[138:141], v[92:95], v[16:31]
	v_exp_f32_e32 v108, v108
	v_exp_f32_e32 v109, v109
	v_exp_f32_e32 v110, v110
	v_exp_f32_e32 v111, v111
	ds_read_b128 v[166:169], v187 offset:20480
	ds_read_b128 v[170:173], v187 offset:20992
	s_waitcnt lgkmcnt(12)
	v_mfma_f32_32x32x16_bf16 v[0:15], v[134:137], v[116:119], v[0:15]
	v_exp_f32_e32 v64, v64
	v_exp_f32_e32 v65, v65
	v_exp_f32_e32 v66, v66
	v_exp_f32_e32 v67, v67
	ds_read_b128 v[116:119], v187 offset:22528
	ds_read_b128 v[112:115], v187 offset:23040
	s_waitcnt lgkmcnt(12)
	v_mfma_f32_32x32x16_bf16 v[16:31], v[134:137], v[48:51], v[16:31]
	v_exp_f32_e32 v68, v68
	v_exp_f32_e32 v69, v69
	v_exp_f32_e32 v70, v70
	v_exp_f32_e32 v71, v71
	s_waitcnt lgkmcnt(10)
	v_mfma_f32_32x32x16_bf16 v[0:15], v[130:133], v[52:55], v[0:15]
	v_exp_f32_e32 v72, v72
	v_exp_f32_e32 v73, v73
	v_exp_f32_e32 v74, v74
	v_exp_f32_e32 v75, v75
	s_waitcnt lgkmcnt(8)
	v_mfma_f32_32x32x16_bf16 v[16:31], v[130:133], v[56:59], v[16:31]
	v_exp_f32_e32 v76, v76
	v_exp_f32_e32 v77, v77
	v_exp_f32_e32 v78, v78
	v_exp_f32_e32 v79, v79
	s_waitcnt vmcnt(1) lgkmcnt(0)
	s_barrier
;   #define RESC() do { if constexpr (!NOMAX) if (resc) { asm volatile("s_waitcnt lgkmcnt(0)" ::: "memory"); \
;       _Pragma("unroll") for (int d_ = 0; d_ < 2 * DV2; ++d_) _Pragma("unroll") for (int r = 0; r < 16; ++r) o[d_][r] *= wsf[crow(r, hi)]; } } while (0)
;   #define ROT() do { sl_prev = sl_cur; sl_cur = sl_next; sl_next = (sl_next == (NSLOT - 1) * SLOTB) ? 0 : sl_next + SLOTB; } while (0)
;   #define ENDW(tt) do { if constexpr (DV2 == 2) { if ((tt) + 3 < NT) { WAIT_BAR(3); } else if ((tt) + 2 < NT) { WAIT_BAR(2); } else { WAIT_BAR(0); } } \
;     else { if ((tt) + 3 < NT) { WAIT_BAR(2); } else if ((tt) + 2 < NT) { WAIT_BAR(1); } else { WAIT_BAR(0); } } } while (0)
;     ...
;   for (; t + 1 < NT; t += 2) {
;     STEP(pB0, pB1, pA0, pA1, t, (t + 3 < NT), (t + 1 < NT), (t + 1 < NT));         ENDW(t);     RESC(); ROT();
;     STEP(pA0, pA1, pB0, pB1, t + 1, (t + 4 < NT), (t + 2 < NT), (t + 2 < NT));     ENDW(t + 1); RESC(); ROT();
;   }
;   STEP(pB0, pB1, pA0, pA1, NT - 1, false, false, false); RESC();
	ds_read_b64_tr_b16 v[174:175], v189 offset:32768
	ds_read_b64_tr_b16 v[176:177], v189 offset:33280
	v_add_f32_e32 v48, v96, v97
	v_add_f32_e32 v48, v98, v48
	v_add_f32_e32 v48, v99, v48
	v_add_f32_e32 v48, v100, v48
	v_add_f32_e32 v48, v101, v48
	v_cvt_pk_bf16_f32 v142, v96, v97
	v_cvt_pk_bf16_f32 v143, v98, v99
	s_waitcnt lgkmcnt(9)
	v_mfma_f32_32x32x16_bf16 v[80:95], v[60:63], v[158:161], v[32:47]
	ds_read_b64_tr_b16 v[96:97], v189 offset:36864
	ds_read_b64_tr_b16 v[98:99], v189 offset:37376
	v_add_f32_e32 v48, v102, v48
	v_add_f32_e32 v48, v103, v48
	v_add_f32_e32 v48, v104, v48
	v_add_f32_e32 v129, v105, v48
	s_waitcnt lgkmcnt(10)
	v_mfma_f32_32x32x16_bf16 v[48:63], v[120:123], v[158:161], v[32:47]
	v_cvt_pk_bf16_f32 v144, v100, v101
	v_cvt_pk_bf16_f32 v145, v102, v103
	ds_read_b64_tr_b16 v[100:101], v189 offset:33792
	ds_read_b64_tr_b16 v[102:103], v189 offset:34304
	v_add_f32_e32 v120, v106, v129
	v_add_f32_e32 v120, v107, v120
	v_add_f32_e32 v120, v108, v120
	v_add_f32_e32 v120, v109, v120
	v_cvt_pk_bf16_f32 v138, v104, v105
	v_cvt_pk_bf16_f32 v139, v106, v107
	s_waitcnt lgkmcnt(11)
	v_mfma_f32_32x32x16_bf16 v[80:95], v[124:127], v[154:157], v[80:95]
	ds_read_b64_tr_b16 v[104:105], v189 offset:37888
	ds_read_b64_tr_b16 v[106:107], v189 offset:38400
	s_waitcnt lgkmcnt(12)
	v_mfma_f32_32x32x16_bf16 v[48:63], v[162:165], v[154:157], v[48:63]
	v_add_f32_e32 v120, v110, v120
	v_add_f32_e32 v120, v111, v120
	v_add_f32_e32 v120, v64, v120
	v_add_f32_e32 v124, v65, v120
	v_cvt_pk_bf16_f32 v140, v108, v109
	v_cvt_pk_bf16_f32 v141, v110, v111
	ds_read_b64_tr_b16 v[120:121], v189 offset:34816
	ds_read_b64_tr_b16 v[122:123], v189 offset:35328
	v_add_f32_e32 v108, v66, v124
	v_add_f32_e32 v108, v67, v108
	v_add_f32_e32 v108, v68, v108
	v_add_f32_e32 v108, v69, v108
	v_cvt_pk_bf16_f32 v134, v64, v65
	v_cvt_pk_bf16_f32 v135, v66, v67
	s_waitcnt lgkmcnt(13)
	v_mfma_f32_32x32x16_bf16 v[80:95], v[166:169], v[150:153], v[80:95]
	ds_read_b64_tr_b16 v[64:65], v189 offset:38912
	ds_read_b64_tr_b16 v[66:67], v189 offset:39424
	s_waitcnt lgkmcnt(14)
	v_mfma_f32_32x32x16_bf16 v[48:63], v[170:173], v[150:153], v[48:63]
	v_add_f32_e32 v108, v70, v108
	v_add_f32_e32 v108, v71, v108
	v_add_f32_e32 v108, v72, v108
	v_add_f32_e32 v108, v73, v108
	v_cvt_pk_bf16_f32 v136, v68, v69
	v_cvt_pk_bf16_f32 v137, v70, v71
	ds_read_b64_tr_b16 v[68:69], v189 offset:35840
	ds_read_b64_tr_b16 v[70:71], v189 offset:36352
	v_add_f32_e32 v108, v74, v108
	v_add_f32_e32 v108, v75, v108
	v_add_f32_e32 v108, v76, v108
	v_add_f32_e32 v108, v77, v108
	v_cvt_pk_bf16_f32 v130, v72, v73
	v_cvt_pk_bf16_f32 v131, v74, v75
	s_waitcnt lgkmcnt(14)
	v_mfma_f32_32x32x16_bf16 v[80:95], v[116:119], v[146:149], v[80:95]
	ds_read_b64_tr_b16 v[72:73], v189 offset:39936
	ds_read_b64_tr_b16 v[74:75], v189 offset:40448
	v_mfma_f32_32x32x16_bf16 v[48:63], v[112:115], v[146:149], v[48:63]
	v_add_f32_e32 v108, v78, v108
	v_add_f32_e32 v108, v79, v108
	v_add_f32_e32 v108, 0, v108
	v_cvt_pk_bf16_f32 v132, v76, v77
	v_cvt_pk_bf16_f32 v133, v78, v79
	s_add_u32 s8, s8, 0xbd0000
	s_addc_u32 s9, s9, 0
	s_mov_b32 s10, m0
	s_mov_b32 m0, s15
	s_nop 0
	global_load_lds_dwordx4 v185, s[8:9]
	s_mov_b32 m0, s10
	v_add_f32_e32 v108, v128, v108
	s_waitcnt lgkmcnt(14)
	v_mfma_f32_32x32x16_bf16 v[0:15], v[142:145], v[174:177], v[0:15]
	v_exp_f32_e32 v80, v80
	v_exp_f32_e32 v81, v81
	v_exp_f32_e32 v82, v82
	v_exp_f32_e32 v83, v83
	s_waitcnt lgkmcnt(12)
	v_mfma_f32_32x32x16_bf16 v[16:31], v[142:145], v[96:99], v[16:31]
	v_exp_f32_e32 v84, v84
	v_exp_f32_e32 v85, v85
	v_exp_f32_e32 v86, v86
	v_exp_f32_e32 v87, v87
	ds_read_b128 v[110:113], v187
	ds_read_b128 v[114:117], v187 offset:512
	s_waitcnt lgkmcnt(12)
	v_mfma_f32_32x32x16_bf16 v[0:15], v[138:141], v[100:103], v[0:15]
	v_exp_f32_e32 v88, v88
	v_exp_f32_e32 v89, v89
	v_exp_f32_e32 v90, v90
	v_exp_f32_e32 v91, v91
	ds_read_b128 v[124:127], v187 offset:2048
	ds_read_b128 v[162:165], v187 offset:2560
	s_waitcnt lgkmcnt(12)
	v_mfma_f32_32x32x16_bf16 v[16:31], v[138:141], v[104:107], v[16:31]
	v_exp_f32_e32 v92, v92
	v_exp_f32_e32 v93, v93
	v_exp_f32_e32 v94, v94
	v_exp_f32_e32 v95, v95
	ds_read_b128 v[166:169], v187 offset:4096
	ds_read_b128 v[170:173], v187 offset:4608
	s_waitcnt lgkmcnt(12)
	v_mfma_f32_32x32x16_bf16 v[0:15], v[134:137], v[120:123], v[0:15]
	v_exp_f32_e32 v48, v48
	v_exp_f32_e32 v49, v49
	v_exp_f32_e32 v50, v50
	v_exp_f32_e32 v51, v51
	ds_read_b128 v[118:121], v187 offset:6144
	ds_read_b128 v[104:107], v187 offset:6656
	s_waitcnt lgkmcnt(12)
	v_mfma_f32_32x32x16_bf16 v[16:31], v[134:137], v[64:67], v[16:31]
	v_exp_f32_e32 v52, v52
	v_exp_f32_e32 v53, v53
	v_exp_f32_e32 v54, v54
	v_exp_f32_e32 v55, v55
	s_waitcnt lgkmcnt(10)
	v_mfma_f32_32x32x16_bf16 v[0:15], v[130:133], v[68:71], v[0:15]
	v_exp_f32_e32 v56, v56
	v_exp_f32_e32 v57, v57
	v_exp_f32_e32 v58, v58
	v_exp_f32_e32 v59, v59
	s_waitcnt lgkmcnt(8)
	v_mfma_f32_32x32x16_bf16 v[16:31], v[130:133], v[72:75], v[16:31]
	v_exp_f32_e32 v60, v60
	v_exp_f32_e32 v61, v61
	v_exp_f32_e32 v62, v62
	v_exp_f32_e32 v63, v63
	s_waitcnt vmcnt(0) lgkmcnt(0)
	s_barrier
;   #define RESC() do { if constexpr (!NOMAX) if (resc) { asm volatile("s_waitcnt lgkmcnt(0)" ::: "memory"); \
;       _Pragma("unroll") for (int d_ = 0; d_ < 2 * DV2; ++d_) _Pragma("unroll") for (int r = 0; r < 16; ++r) o[d_][r] *= wsf[crow(r, hi)]; } } while (0)
;     ...
;   STEP(pB0, pB1, pA0, pA1, NT - 1, false, false, false); RESC();
	ds_read_b64_tr_b16 v[96:97], v189 offset:40960
	ds_read_b64_tr_b16 v[98:99], v189 offset:41472
	v_add_f32_e32 v64, v80, v81
	v_add_f32_e32 v64, v82, v64
	v_add_f32_e32 v64, v83, v64
	v_add_f32_e32 v64, v84, v64
	v_add_f32_e32 v100, v85, v64
	v_cvt_pk_bf16_f32 v142, v80, v81
	v_cvt_pk_bf16_f32 v143, v82, v83
	s_waitcnt lgkmcnt(9)
	v_mfma_f32_32x32x16_bf16 v[64:79], v[110:113], v[158:161], v[32:47]
	ds_read_b64_tr_b16 v[80:81], v189 offset:45056
	ds_read_b64_tr_b16 v[82:83], v189 offset:45568
	s_waitcnt lgkmcnt(10)
	v_mfma_f32_32x32x16_bf16 v[32:47], v[114:117], v[158:161], v[32:47]
	v_add_f32_e32 v100, v86, v100
	v_add_f32_e32 v100, v87, v100
	v_add_f32_e32 v100, v88, v100
	v_add_f32_e32 v109, v89, v100
	v_cvt_pk_bf16_f32 v144, v84, v85
	v_cvt_pk_bf16_f32 v145, v86, v87
	ds_read_b64_tr_b16 v[100:101], v189 offset:41984
	ds_read_b64_tr_b16 v[102:103], v189 offset:42496
	v_add_f32_e32 v84, v90, v109
	v_add_f32_e32 v84, v91, v84
	v_add_f32_e32 v84, v92, v84
	v_add_f32_e32 v109, v93, v84
	v_cvt_pk_bf16_f32 v138, v88, v89
	v_cvt_pk_bf16_f32 v139, v90, v91
	s_waitcnt lgkmcnt(11)
	v_mfma_f32_32x32x16_bf16 v[64:79], v[124:127], v[154:157], v[64:79]
	ds_read_b64_tr_b16 v[84:85], v189 offset:46080
	ds_read_b64_tr_b16 v[86:87], v189 offset:46592
	s_waitcnt lgkmcnt(12)
	v_mfma_f32_32x32x16_bf16 v[32:47], v[162:165], v[154:157], v[32:47]
	v_add_f32_e32 v88, v94, v109
	v_add_f32_e32 v88, v95, v88
	v_add_f32_e32 v88, v48, v88
	v_add_f32_e32 v109, v49, v88
	v_cvt_pk_bf16_f32 v140, v92, v93
	v_cvt_pk_bf16_f32 v141, v94, v95
	ds_read_b64_tr_b16 v[88:89], v189 offset:43008
	ds_read_b64_tr_b16 v[90:91], v189 offset:43520
	v_add_f32_e32 v92, v50, v109
	v_add_f32_e32 v92, v51, v92
	v_add_f32_e32 v92, v52, v92
	v_add_f32_e32 v92, v53, v92
	v_cvt_pk_bf16_f32 v134, v48, v49
	v_cvt_pk_bf16_f32 v135, v50, v51
	s_waitcnt lgkmcnt(13)
	v_mfma_f32_32x32x16_bf16 v[64:79], v[166:169], v[150:153], v[64:79]
	ds_read_b64_tr_b16 v[48:49], v189 offset:47104
	ds_read_b64_tr_b16 v[50:51], v189 offset:47616
	s_waitcnt lgkmcnt(14)
	v_mfma_f32_32x32x16_bf16 v[32:47], v[170:173], v[150:153], v[32:47]
	v_add_f32_e32 v92, v54, v92
	v_add_f32_e32 v92, v55, v92
	v_add_f32_e32 v92, v56, v92
	v_add_f32_e32 v109, v57, v92
	v_cvt_pk_bf16_f32 v136, v52, v53
	v_cvt_pk_bf16_f32 v137, v54, v55
	ds_read_b64_tr_b16 v[92:93], v189 offset:44032
	ds_read_b64_tr_b16 v[94:95], v189 offset:44544
	v_add_f32_e32 v52, v58, v109
	v_add_f32_e32 v52, v59, v52
	v_add_f32_e32 v52, v60, v52
	v_add_f32_e32 v109, v61, v52
	v_cvt_pk_bf16_f32 v130, v56, v57
	v_cvt_pk_bf16_f32 v131, v58, v59
	s_waitcnt lgkmcnt(14)
	v_mfma_f32_32x32x16_bf16 v[64:79], v[118:121], v[146:149], v[64:79]
	ds_read_b64_tr_b16 v[52:53], v189 offset:48128
	ds_read_b64_tr_b16 v[54:55], v189 offset:48640
	v_mfma_f32_32x32x16_bf16 v[32:47], v[104:107], v[146:149], v[32:47]
	v_add_f32_e32 v56, v62, v109
	v_add_f32_e32 v56, v63, v56
	v_add_f32_e32 v56, 0, v56
	v_cvt_pk_bf16_f32 v132, v60, v61
	v_cvt_pk_bf16_f32 v133, v62, v63
	s_nop 3
	v_exp_f32_e32 v64, v64
	v_exp_f32_e32 v65, v65
	v_exp_f32_e32 v66, v66
	v_exp_f32_e32 v67, v67
	s_nop 0
	v_exp_f32_e32 v68, v68
	v_exp_f32_e32 v69, v69
	v_exp_f32_e32 v70, v70
	v_exp_f32_e32 v71, v71
	s_nop 0
	v_exp_f32_e32 v72, v72
	v_exp_f32_e32 v73, v73
	v_exp_f32_e32 v74, v74
	v_exp_f32_e32 v75, v75
	s_nop 0
	v_exp_f32_e32 v76, v76
	v_exp_f32_e32 v77, v77
	v_exp_f32_e32 v78, v78
	v_exp_f32_e32 v79, v79
	v_exp_f32_e32 v32, v32
	v_exp_f32_e32 v33, v33
	v_exp_f32_e32 v34, v34
	v_exp_f32_e32 v35, v35
	s_nop 0
	v_exp_f32_e32 v36, v36
	v_exp_f32_e32 v37, v37
	v_exp_f32_e32 v38, v38
	v_exp_f32_e32 v39, v39
	s_nop 0
	v_exp_f32_e32 v40, v40
	v_exp_f32_e32 v41, v41
	v_exp_f32_e32 v42, v42
	v_exp_f32_e32 v43, v43
	s_nop 0
	v_exp_f32_e32 v44, v44
	v_exp_f32_e32 v45, v45
	v_exp_f32_e32 v46, v46
	v_exp_f32_e32 v47, v47
	s_waitcnt lgkmcnt(14)
; #define SBAR() __builtin_amdgcn_sched_barrier(0)
;   #define PKW(P, B) cvtpk_s(P[B], P[B + 1])
;     ...
;   { float sacc = pB0[0] + pB0[1]; _Pragma("unroll") for (int r = 2; r < 16; ++r) sacc += pB0[r]; _Pragma("unroll") for (int r = 0; r < 16; ++r) sacc += pB1[r]; l_reg += sacc;
;     pw0 = (u32x4){PKW(pB0, 0), PKW(pB0, 2), PKW(pB0, 4), PKW(pB0, 6)}; pw1 = (u32x4){PKW(pB0, 8), PKW(pB0, 10), PKW(pB0, 12), PKW(pB0, 14)}; pw2 = (u32x4){PKW(pB1, 0), PKW(pB1, 2), PKW(pB1, 4), PKW(pB1, 6)}; pw3 = (u32x4){PKW(pB1, 8), PKW(pB1, 10), PKW(pB1, 12), PKW(pB1, 14)};
;     SBAR(); pv(o, vb0 + DV2 * sl_cur, PAF(0), PAF(1), PAF(2), PAF(3)); if constexpr (DV2 == 2) pv(o + 2, vb0 + DV2 * sl_cur + 8192, PAF(0), PAF(1), PAF(2), PAF(3)); }
;     ...
;   { auto rr = __builtin_amdgcn_permlane32_swap(__float_as_uint(l_reg), __float_as_uint(l_reg), false, false); l_reg = __uint_as_float(rr[0]) + __uint_as_float(rr[1]); }
;   int lane_e; asm volatile("v_mbcnt_lo_u32_b32 %0, -1, 0\n\tv_mbcnt_hi_u32_b32 %0, -1, %0" : "=v"(lane_e));
;   const int r32e = lane_e & 31, hie = lane_e >> 5;
;   if (hie == 0) wsf[32 + r32e] = l_reg; asm volatile("s_waitcnt lgkmcnt(0)" ::: "memory");
	v_mfma_f32_32x32x16_bf16 v[0:15], v[142:145], v[96:99], v[0:15]
	v_add_f32_e32 v57, v64, v65
	v_add_f32_e32 v57, v66, v57
	v_add_f32_e32 v57, v67, v57
	v_add_f32_e32 v57, v68, v57
	v_add_f32_e32 v57, v69, v57
	v_add_f32_e32 v57, v70, v57
	v_add_f32_e32 v57, v71, v57
	s_waitcnt lgkmcnt(12)
	v_mfma_f32_32x32x16_bf16 v[16:31], v[142:145], v[80:83], v[16:31]
	v_add_f32_e32 v57, v72, v57
	v_add_f32_e32 v57, v73, v57
	v_add_f32_e32 v57, v74, v57
	v_add_f32_e32 v57, v75, v57
	v_add_f32_e32 v57, v76, v57
	v_add_f32_e32 v57, v77, v57
	v_add_f32_e32 v57, v78, v57
	s_waitcnt lgkmcnt(10)
	v_mfma_f32_32x32x16_bf16 v[0:15], v[138:141], v[100:103], v[0:15]
	v_add_f32_e32 v57, v79, v57
	v_add_f32_e32 v57, v32, v57
	v_add_f32_e32 v57, v33, v57
	v_add_f32_e32 v57, v34, v57
	v_add_f32_e32 v57, v35, v57
	v_add_f32_e32 v57, v36, v57
	v_add_f32_e32 v57, v37, v57
	s_waitcnt lgkmcnt(8)
	v_mfma_f32_32x32x16_bf16 v[16:31], v[138:141], v[84:87], v[16:31]
	v_add_f32_e32 v57, v38, v57
	v_add_f32_e32 v57, v39, v57
	v_add_f32_e32 v57, v40, v57
	v_add_f32_e32 v57, v41, v57
	v_add_f32_e32 v57, v42, v57
	v_add_f32_e32 v57, v43, v57
	v_add_f32_e32 v57, v44, v57
	s_waitcnt lgkmcnt(6)
	v_mfma_f32_32x32x16_bf16 v[0:15], v[134:137], v[88:91], v[0:15]
	v_add_f32_e32 v57, v45, v57
	v_add_f32_e32 v57, v46, v57
	v_add_f32_e32 v57, v47, v57
	v_add_f32_e32 v56, v108, v56
	v_add_f32_e32 v56, v56, v57
	v_cvt_pk_bf16_f32 v32, v32, v33
	v_cvt_pk_bf16_f32 v33, v34, v35
	s_waitcnt lgkmcnt(4)
	v_mfma_f32_32x32x16_bf16 v[16:31], v[134:137], v[48:51], v[16:31]
	v_cvt_pk_bf16_f32 v58, v64, v65
	v_cvt_pk_bf16_f32 v59, v66, v67
	v_cvt_pk_bf16_f32 v60, v68, v69
	v_cvt_pk_bf16_f32 v61, v70, v71
	v_cvt_pk_bf16_f32 v62, v72, v73
	v_cvt_pk_bf16_f32 v63, v74, v75
	v_cvt_pk_bf16_f32 v64, v76, v77
	s_waitcnt lgkmcnt(2)
	v_mfma_f32_32x32x16_bf16 v[0:15], v[130:133], v[92:95], v[0:15]
	v_cvt_pk_bf16_f32 v65, v78, v79
	v_cvt_pk_bf16_f32 v34, v36, v37
	v_cvt_pk_bf16_f32 v35, v38, v39
	v_cvt_pk_bf16_f32 v36, v40, v41
	v_cvt_pk_bf16_f32 v37, v42, v43
	v_cvt_pk_bf16_f32 v38, v44, v45
	v_cvt_pk_bf16_f32 v39, v46, v47
	s_waitcnt lgkmcnt(0)
	v_mfma_f32_32x32x16_bf16 v[16:31], v[130:133], v[52:55], v[16:31]
	ds_read_b64_tr_b16 v[40:41],v188 offset:0
	ds_read_b64_tr_b16 v[42:43],v188 offset:512
	ds_read_b64_tr_b16 v[44:45],v188 offset:1024
	ds_read_b64_tr_b16 v[46:47],v188 offset:1536
	ds_read_b64_tr_b16 v[48:49],v188 offset:2048
	ds_read_b64_tr_b16 v[50:51],v188 offset:2560
	ds_read_b64_tr_b16 v[52:53],v188 offset:3072
	ds_read_b64_tr_b16 v[54:55],v188 offset:3584
	s_waitcnt lgkmcnt(0)
	s_nop 0
	v_mfma_f32_32x32x16_bf16 v[0:15], v[58:61], v[40:43], v[0:15]
	ds_read_b64_tr_b16 v[40:41],v188 offset:4096
	ds_read_b64_tr_b16 v[42:43],v188 offset:4608
	v_mfma_f32_32x32x16_bf16 v[0:15], v[62:65], v[44:47], v[0:15]
	ds_read_b64_tr_b16 v[44:45],v188 offset:5120
	ds_read_b64_tr_b16 v[46:47],v188 offset:5632
	v_mfma_f32_32x32x16_bf16 v[0:15], v[32:35], v[48:51], v[0:15]
	ds_read_b64_tr_b16 v[48:49],v188 offset:6144
	ds_read_b64_tr_b16 v[50:51],v188 offset:6656
	v_mfma_f32_32x32x16_bf16 v[0:15], v[36:39], v[52:55], v[0:15]
	ds_read_b64_tr_b16 v[52:53],v188 offset:7168
	ds_read_b64_tr_b16 v[54:55],v188 offset:7680
	s_waitcnt lgkmcnt(0)
	v_mfma_f32_32x32x16_bf16 v[16:31], v[58:61], v[40:43], v[16:31]
	v_mfma_f32_32x32x16_bf16 v[16:31], v[62:65], v[44:47], v[16:31]
	v_mfma_f32_32x32x16_bf16 v[16:31], v[32:35], v[48:51], v[16:31]
	v_mov_b32_e32 v33, v56
	s_nop 1
	v_permlane32_swap_b32_e32 v56, v33
	v_mbcnt_lo_u32_b32 v32, -1, 0
	v_mbcnt_hi_u32_b32 v32, -1, v32
	s_nop 0
	v_cmp_gt_u32_e32 vcc, 32, v32
	v_mfma_f32_32x32x16_bf16 v[16:31], v[36:39], v[52:55], v[16:31]
	s_and_saveexec_b64 s[8:9], vcc
	s_cbranch_execz .LBB0_968
	v_add_f32_e32 v33, v56, v33
	v_lshl_add_u32 v34, v32, 2, s16
	ds_write_b32 v34, v33 offset:49280
	s_branch .LBB0_968
